# attention: first three V fragments (ds_read_b64_tr) issued early in the QK block into freed registers v[52:63], counted lgkmcnt waits re-derived
# baseline (speedup 1.0000x reference)
.LBB0_727:
	v_cmp_lt_f32_e32 vcc, s99, v48
	s_cbranch_vccz .LBB0_729
	v_max_f32_e32 v32, v48, v48
	v_max_f32_e32 v33, 0, v32
	v_exp_f32_e64 v32, -v33
	v_add_f32_e32 v230, v230, v33
	v_xor_b32_e32 v48, 0x80000000, v230
	v_sub_f32_e32 v79, v79, v33
	v_sub_f32_e32 v78, v78, v33
	v_sub_f32_e32 v77, v77, v33
	v_sub_f32_e32 v76, v76, v33
	v_sub_f32_e32 v75, v75, v33
	v_sub_f32_e32 v74, v74, v33
	v_sub_f32_e32 v73, v73, v33
	v_sub_f32_e32 v72, v72, v33
	v_sub_f32_e32 v71, v71, v33
	v_sub_f32_e32 v70, v70, v33
	v_sub_f32_e32 v69, v69, v33
	v_sub_f32_e32 v68, v68, v33
	v_sub_f32_e32 v67, v67, v33
	v_sub_f32_e32 v66, v66, v33
	v_sub_f32_e32 v65, v65, v33
	v_sub_f32_e32 v64, v64, v33
	v_sub_f32_e32 v111, v111, v33
	v_sub_f32_e32 v110, v110, v33
	v_sub_f32_e32 v109, v109, v33
	v_sub_f32_e32 v108, v108, v33
	v_sub_f32_e32 v107, v107, v33
	v_sub_f32_e32 v106, v106, v33
	v_sub_f32_e32 v105, v105, v33
	v_sub_f32_e32 v104, v104, v33
	v_sub_f32_e32 v103, v103, v33
	v_sub_f32_e32 v102, v102, v33
	v_sub_f32_e32 v101, v101, v33
	v_sub_f32_e32 v100, v100, v33
	v_sub_f32_e32 v99, v99, v33
	v_sub_f32_e32 v98, v98, v33
	v_sub_f32_e32 v97, v97, v33
	v_sub_f32_e32 v96, v96, v33
	v_pk_mul_f32 v[14:15], v[32:33], v[14:15] op_sel_hi:[0,1]
	v_pk_mul_f32 v[12:13], v[32:33], v[12:13] op_sel_hi:[0,1]
	v_pk_mul_f32 v[10:11], v[32:33], v[10:11] op_sel_hi:[0,1]
	v_pk_mul_f32 v[8:9], v[32:33], v[8:9] op_sel_hi:[0,1]
	v_pk_mul_f32 v[6:7], v[32:33], v[6:7] op_sel_hi:[0,1]
	v_pk_mul_f32 v[4:5], v[32:33], v[4:5] op_sel_hi:[0,1]
	v_pk_mul_f32 v[2:3], v[32:33], v[2:3] op_sel_hi:[0,1]
	v_pk_mul_f32 v[0:1], v[32:33], v[0:1] op_sel_hi:[0,1]
	v_pk_mul_f32 v[30:31], v[32:33], v[30:31] op_sel_hi:[0,1]
	v_pk_mul_f32 v[28:29], v[32:33], v[28:29] op_sel_hi:[0,1]
	v_pk_mul_f32 v[26:27], v[32:33], v[26:27] op_sel_hi:[0,1]
	v_pk_mul_f32 v[24:25], v[32:33], v[24:25] op_sel_hi:[0,1]
	v_pk_mul_f32 v[22:23], v[32:33], v[22:23] op_sel_hi:[0,1]
	v_pk_mul_f32 v[20:21], v[32:33], v[20:21] op_sel_hi:[0,1]
	v_pk_mul_f32 v[18:19], v[32:33], v[18:19] op_sel_hi:[0,1]
	v_pk_mul_f32 v[16:17], v[32:33], v[16:17] op_sel_hi:[0,1]
	v_mul_f32_e32 v234, v234, v32
	v_mov_b32_e32 v49, v48
	v_mov_b32_e32 v50, v48
	v_mov_b32_e32 v51, v48
	v_mov_b32_e32 v32, v48
	v_mov_b32_e32 v33, v48
	v_mov_b32_e32 v34, v48
	v_mov_b32_e32 v35, v48
	v_mov_b32_e32 v36, v48
	v_mov_b32_e32 v37, v48
	v_mov_b32_e32 v38, v48
	v_mov_b32_e32 v39, v48
	v_mov_b32_e32 v40, v48
	v_mov_b32_e32 v41, v48
	v_mov_b32_e32 v42, v48
	v_mov_b32_e32 v43, v48
	v_mov_b32_e32 v44, v48
	v_mov_b32_e32 v45, v48
	v_mov_b32_e32 v46, v48
	v_mov_b32_e32 v47, v48
	s_branch .LBB0_730
.LBB0_729:
.LBB0_730:
	s_add_i32 s25, s60, 1
	s_and_b32 s24, s25, 3
	s_mul_i32 s23, s24, 0x3400
	v_add_u32_e32 v80, s23, v227
	ds_read_b128 v[164:167], v80
	ds_read_b128 v[168:171], v80 offset:32
	ds_read_b128 v[172:175], v80 offset:6656
	ds_read_b128 v[176:179], v80 offset:6688
	ds_read_b128 v[180:183], v80 offset:64
	ds_read_b128 v[184:187], v80 offset:96
	ds_read_b128 v[188:191], v80 offset:6720
	ds_read_b128 v[192:195], v80 offset:6752
	ds_read_b128 v[236:239], v80 offset:128
	ds_read_b128 v[240:243], v80 offset:160
	ds_read_b128 v[244:247], v80 offset:6784
	ds_read_b128 v[160:163], v80 offset:6816
	s_and_b32 s23, s60, 2
	s_mul_i32 s26, s23, 0x3000
	v_add_u32_e32 v253, s26, v232
	s_waitcnt lgkmcnt(11)
	v_mfma_f32_32x32x16_bf16 v[80:95], v[164:167], v[112:115], v[32:47]
	v_exp_f32_e32 v64, v64
	v_exp_f32_e32 v66, v66
	v_exp_f32_e32 v68, v68
	v_exp_f32_e32 v164, v96
	v_exp_f32_e32 v65, v65
	v_exp_f32_e32 v165, v97
	v_exp_f32_e32 v70, v70
	v_add_f32_e32 v96, v66, v64
	v_exp_f32_e32 v67, v67
	v_add_f32_e32 v96, v68, v96
	v_add_f32_e32 v96, v70, v96
	s_waitcnt lgkmcnt(10)
	v_mfma_f32_32x32x16_bf16 v[80:95], v[168:171], v[116:119], v[80:95]
	ds_read_b64_tr_b16 v[52:53], v253 offset:53248
	ds_read_b64_tr_b16 v[54:55], v253 offset:54784
	ds_read_b64_tr_b16 v[56:57], v253 offset:53312
	ds_read_b64_tr_b16 v[58:59], v253 offset:54848
	ds_read_b64_tr_b16 v[60:61], v253 offset:56320
	ds_read_b64_tr_b16 v[62:63], v253 offset:57856
	v_exp_f32_e32 v169, v99
	v_exp_f32_e32 v168, v98
	v_add_f32_e32 v98, v67, v65
	v_exp_f32_e32 v166, v100
	v_add_f32_e32 v99, v169, v165
	v_exp_f32_e32 v69, v69
	v_exp_f32_e32 v167, v101
	v_exp_f32_e32 v170, v102
	v_add_f32_e32 v97, v168, v164
	v_add_f32_e32 v97, v166, v97
	v_add_f32_e32 v98, v69, v98
	v_add_f32_e32 v99, v167, v99
	v_add_f32_e32 v97, v170, v97
	s_waitcnt lgkmcnt(13)
	v_mfma_f32_32x32x16_bf16 v[80:95], v[180:183], v[120:123], v[80:95]
	v_exp_f32_e32 v71, v71
	v_exp_f32_e32 v171, v103
	v_exp_f32_e32 v180, v72
	v_exp_f32_e32 v181, v104
	v_exp_f32_e32 v182, v73
	v_exp_f32_e32 v183, v105
	v_add_f32_e32 v98, v71, v98
	v_add_f32_e32 v99, v171, v99
	v_add_f32_e32 v72, v180, v96
	v_add_f32_e32 v73, v181, v97
	v_add_f32_e32 v96, v182, v98
	v_add_f32_e32 v97, v183, v99
	v_exp_f32_e32 v235, v76
	v_cvt_pk_bf16_f32 v76, v180, v182
	s_waitcnt lgkmcnt(12)
	v_mfma_f32_32x32x16_bf16 v[80:95], v[184:187], v[124:127], v[80:95]
	v_exp_f32_e32 v184, v74
	v_exp_f32_e32 v185, v106
	v_exp_f32_e32 v186, v75
	v_exp_f32_e32 v187, v107
	v_add_f32_e32 v72, v184, v72
	v_add_f32_e32 v73, v185, v73
	v_add_f32_e32 v74, v186, v96
	v_add_f32_e32 v75, v187, v97
	v_add_f32_e32 v72, v235, v72
	s_waitcnt lgkmcnt(9)
	v_mfma_f32_32x32x16_bf16 v[80:95], v[236:239], v[128:131], v[80:95]
	v_exp_f32_e32 v237, v77
	v_exp_f32_e32 v236, v108
	v_exp_f32_e32 v238, v109
	v_exp_f32_e32 v239, v78
	v_exp_f32_e32 v79, v79
	v_add_f32_e32 v74, v237, v74
	v_add_f32_e32 v73, v236, v73
	v_add_f32_e32 v75, v238, v75
	v_add_f32_e32 v72, v239, v72
	v_add_f32_e32 v74, v79, v74
	v_cvt_pk_bf16_f32 v77, v184, v186
	v_cvt_pk_bf16_f32 v78, v235, v237
	s_waitcnt lgkmcnt(8)
	v_mfma_f32_32x32x16_bf16 v[80:95], v[240:243], v[132:135], v[80:95]
	v_exp_f32_e32 v240, v110
	v_exp_f32_e32 v241, v111
	v_cvt_pk_bf16_f32 v79, v239, v79
	v_add_f32_e32 v73, v240, v73
	v_add_f32_e32 v75, v241, v75
	v_add_f32_e32 v72, v73, v72
	v_add_f32_e32 v73, v75, v74
	v_cvt_pk_bf16_f32 v74, v68, v69
	v_cvt_pk_bf16_f32 v75, v70, v71
	v_mfma_f32_32x32x16_bf16 v[96:111], v[172:175], v[112:115], v[32:47]
	v_add_f32_e32 v172, v73, v72
	v_cvt_pk_bf16_f32 v72, v64, v65
	v_cvt_pk_bf16_f32 v73, v66, v67
	v_cvt_pk_bf16_f32 v64, v164, v165
	v_cvt_pk_bf16_f32 v65, v168, v169
	v_cvt_pk_bf16_f32 v66, v166, v167
	v_cvt_pk_bf16_f32 v67, v170, v171
	v_mfma_f32_32x32x16_bf16 v[96:111], v[176:179], v[116:119], v[96:111]
	v_cvt_pk_bf16_f32 v68, v181, v183
	v_cvt_pk_bf16_f32 v69, v185, v187
	v_cvt_pk_bf16_f32 v70, v236, v238
	v_cvt_pk_bf16_f32 v71, v240, v241
	v_add_f32_e32 v234, v234, v172
	v_mfma_f32_32x32x16_bf16 v[96:111], v[188:191], v[120:123], v[96:111]
	v_mfma_f32_32x32x16_bf16 v[96:111], v[192:195], v[124:127], v[96:111]
	s_waitcnt lgkmcnt(7)
	v_mfma_f32_32x32x16_bf16 v[96:111], v[244:247], v[128:131], v[96:111]
	s_waitcnt lgkmcnt(6)
	v_mfma_f32_32x32x16_bf16 v[96:111], v[160:163], v[132:135], v[96:111]
	ds_read_b64_tr_b16 v[182:183], v253 offset:57920
	ds_read_b64_tr_b16 v[180:181], v253 offset:56384
	ds_read_b64_tr_b16 v[176:177], v253 offset:59392
	ds_read_b64_tr_b16 v[178:179], v253 offset:60928
	ds_read_b64_tr_b16 v[174:175], v253 offset:60992
	ds_read_b64_tr_b16 v[172:173], v253 offset:59456
	ds_read_b64_tr_b16 v[168:169], v253 offset:62464
	ds_read_b64_tr_b16 v[170:171], v253 offset:64000
	ds_read_b64_tr_b16 v[166:167], v253 offset:64064
	ds_read_b64_tr_b16 v[164:165], v253 offset:62528
	s_cmp_lt_u32 s25, s7
	s_cbranch_scc1 .LBB0_732
	v_add_u32_e32 v160, 32, v233
	v_cmp_le_i32_e32 vcc, v160, v229
	v_add_u32_e32 v160, 33, v233
	s_nop 0
	v_cndmask_b32_e32 v96, v224, v96, vcc
	v_cmp_lt_i32_e32 vcc, v233, v229
	s_nop 1
	v_cndmask_b32_e32 v81, v224, v81, vcc
	v_cmp_le_i32_e32 vcc, v233, v229
	s_nop 1
	v_cndmask_b32_e32 v80, v224, v80, vcc
	v_cmp_le_i32_e32 vcc, v160, v229
	v_add_u32_e32 v160, 2, v233
	s_nop 0
	v_cndmask_b32_e32 v97, v224, v97, vcc
	v_cmp_le_i32_e32 vcc, v160, v229
	v_add_u32_e32 v160, 34, v233
	s_nop 0
	v_cndmask_b32_e32 v82, v224, v82, vcc
	v_cmp_le_i32_e32 vcc, v160, v229
	v_add_u32_e32 v160, 3, v233
	s_nop 0
	v_cndmask_b32_e32 v98, v224, v98, vcc
	v_cmp_le_i32_e32 vcc, v160, v229
	v_add_u32_e32 v160, 35, v233
	s_nop 0
	v_cndmask_b32_e32 v83, v224, v83, vcc
	v_cmp_le_i32_e32 vcc, v160, v229
	v_add_u32_e32 v160, 8, v233
	s_nop 0
	v_cndmask_b32_e32 v99, v224, v99, vcc
	v_cmp_le_i32_e32 vcc, v160, v229
	v_add_u32_e32 v160, 40, v233
	s_nop 0
	v_cndmask_b32_e32 v84, v224, v84, vcc
	v_cmp_le_i32_e32 vcc, v160, v229
	v_add_u32_e32 v160, 9, v233
	s_nop 0
	v_cndmask_b32_e32 v100, v224, v100, vcc
	v_cmp_le_i32_e32 vcc, v160, v229
	v_add_u32_e32 v160, 41, v233
	s_nop 0
	v_cndmask_b32_e32 v85, v224, v85, vcc
	v_cmp_le_i32_e32 vcc, v160, v229
	v_add_u32_e32 v160, 10, v233
	s_nop 0
	v_cndmask_b32_e32 v101, v224, v101, vcc
	v_cmp_le_i32_e32 vcc, v160, v229
	v_add_u32_e32 v160, 42, v233
	s_nop 0
	v_cndmask_b32_e32 v86, v224, v86, vcc
	v_cmp_le_i32_e32 vcc, v160, v229
	v_add_u32_e32 v160, 11, v233
	s_nop 0
	v_cndmask_b32_e32 v102, v224, v102, vcc
	v_cmp_le_i32_e32 vcc, v160, v229
	v_add_u32_e32 v160, 43, v233
	s_nop 0
	v_cndmask_b32_e32 v87, v224, v87, vcc
	v_cmp_le_i32_e32 vcc, v160, v229
	v_add_u32_e32 v160, 16, v233
	s_nop 0
	v_cndmask_b32_e32 v103, v224, v103, vcc
	v_cmp_le_i32_e32 vcc, v160, v229
	v_add_u32_e32 v160, 48, v233
	s_nop 0
	v_cndmask_b32_e32 v88, v224, v88, vcc
	v_cmp_le_i32_e32 vcc, v160, v229
	v_add_u32_e32 v160, 17, v233
	s_nop 0
	v_cndmask_b32_e32 v104, v224, v104, vcc
	v_cmp_le_i32_e32 vcc, v160, v229
	v_add_u32_e32 v160, 49, v233
	s_nop 0
	v_cndmask_b32_e32 v89, v224, v89, vcc
	v_cmp_le_i32_e32 vcc, v160, v229
	v_add_u32_e32 v160, 18, v233
	s_nop 0
	v_cndmask_b32_e32 v105, v224, v105, vcc
	v_cmp_le_i32_e32 vcc, v160, v229
	v_add_u32_e32 v160, 50, v233
	s_nop 0
	v_cndmask_b32_e32 v90, v224, v90, vcc
	v_cmp_le_i32_e32 vcc, v160, v229
	v_add_u32_e32 v160, 19, v233
	s_nop 0
	v_cndmask_b32_e32 v106, v224, v106, vcc
	v_cmp_le_i32_e32 vcc, v160, v229
	v_add_u32_e32 v160, 51, v233
	s_nop 0
	v_cndmask_b32_e32 v91, v224, v91, vcc
	v_cmp_le_i32_e32 vcc, v160, v229
	v_add_u32_e32 v160, 24, v233
	s_nop 0
	v_cndmask_b32_e32 v107, v224, v107, vcc
	v_cmp_le_i32_e32 vcc, v160, v229
	v_add_u32_e32 v160, 56, v233
	s_nop 0
	v_cndmask_b32_e32 v92, v224, v92, vcc
	v_cmp_le_i32_e32 vcc, v160, v229
	v_add_u32_e32 v160, 25, v233
	s_nop 0
	v_cndmask_b32_e32 v108, v224, v108, vcc
	v_cmp_le_i32_e32 vcc, v160, v229
	v_add_u32_e32 v160, 57, v233
	s_nop 0
	v_cndmask_b32_e32 v93, v224, v93, vcc
	v_cmp_le_i32_e32 vcc, v160, v229
	v_add_u32_e32 v160, 26, v233
	s_nop 0
	v_cndmask_b32_e32 v109, v224, v109, vcc
	v_cmp_le_i32_e32 vcc, v160, v229
	v_add_u32_e32 v160, 58, v233
	s_nop 0
	v_cndmask_b32_e32 v94, v224, v94, vcc
	v_cmp_le_i32_e32 vcc, v160, v229
	v_add_u32_e32 v160, 27, v233
	s_nop 0
	v_cndmask_b32_e32 v110, v224, v110, vcc
	v_cmp_le_i32_e32 vcc, v160, v229
	v_add_u32_e32 v160, 59, v233
	s_nop 0
	v_cndmask_b32_e32 v95, v224, v95, vcc
	v_cmp_le_i32_e32 vcc, v160, v229
	s_nop 1
	v_cndmask_b32_e32 v111, v224, v111, vcc
.LBB0_732:
	s_waitcnt lgkmcnt(14)
	v_mfma_f32_32x32x16_bf16 v[0:15], v[52:55], v[72:75], v[0:15]
	v_max_f32_e32 v160, v81, v81
	v_max_f32_e32 v161, v80, v80
	v_max_f32_e32 v160, v161, v160
	s_waitcnt lgkmcnt(12)
	v_mfma_f32_32x32x16_bf16 v[16:31], v[56:59], v[72:75], v[16:31]
	v_max3_f32 v72, v82, v83, v97
	v_max3_f32 v73, v160, v96, v98
	v_max3_f32 v73, v73, v99, v84
	s_waitcnt lgkmcnt(10)
	v_mfma_f32_32x32x16_bf16 v[0:15], v[60:63], v[76:79], v[0:15]
	v_max3_f32 v72, v72, v86, v87
	v_max3_f32 v73, v73, v85, v100
	v_max3_f32 v72, v72, v102, v103
	s_waitcnt lgkmcnt(8)
	v_mfma_f32_32x32x16_bf16 v[16:31], v[180:183], v[76:79], v[16:31]
	v_max3_f32 v73, v73, v101, v88
	v_max3_f32 v72, v72, v90, v91
	v_max3_f32 v73, v73, v89, v104
	s_waitcnt lgkmcnt(6)
	v_mfma_f32_32x32x16_bf16 v[0:15], v[176:179], v[64:67], v[0:15]
	v_max3_f32 v72, v72, v106, v107
	v_max3_f32 v73, v73, v105, v92
	v_max3_f32 v72, v72, v94, v95
	s_waitcnt lgkmcnt(4)
	v_mfma_f32_32x32x16_bf16 v[16:31], v[172:175], v[64:67], v[16:31]
	v_max3_f32 v64, v73, v93, v108
	v_max3_f32 v65, v72, v110, v111
	v_max3_f32 v64, v64, v109, v65
	s_waitcnt lgkmcnt(2)
	v_mfma_f32_32x32x16_bf16 v[0:15], v[168:171], v[68:71], v[0:15]
	v_mov_b32_e32 v65, v64
	s_nop 1
	v_permlane32_swap_b32_e32 v64, v65
	v_max_f32_e32 v65, v65, v65
	v_max_f32_e32 v64, v64, v64
	v_max_f32_e32 v64, v64, v65
	s_waitcnt lgkmcnt(0)
	v_mfma_f32_32x32x16_bf16 v[16:31], v[164:167], v[68:71], v[16:31]
	v_cmp_lt_f32_e32 vcc, s99, v64
	s_cbranch_vccz .LBB0_734
	v_max_f32_e32 v32, v64, v64
	v_max_f32_e32 v32, 0, v32
	v_exp_f32_e64 v34, -v32
	v_add_f32_e32 v230, v230, v32
	v_xor_b32_e32 v48, 0x80000000, v230
	v_pk_add_f32 v[80:81], v[80:81], v[32:33] op_sel_hi:[1,0] neg_lo:[0,1] neg_hi:[0,1]
	v_pk_add_f32 v[96:97], v[96:97], v[32:33] op_sel_hi:[1,0] neg_lo:[0,1] neg_hi:[0,1]
	v_pk_add_f32 v[82:83], v[82:83], v[32:33] op_sel_hi:[1,0] neg_lo:[0,1] neg_hi:[0,1]
	v_pk_add_f32 v[98:99], v[98:99], v[32:33] op_sel_hi:[1,0] neg_lo:[0,1] neg_hi:[0,1]
	v_pk_add_f32 v[84:85], v[84:85], v[32:33] op_sel_hi:[1,0] neg_lo:[0,1] neg_hi:[0,1]
	v_pk_add_f32 v[100:101], v[100:101], v[32:33] op_sel_hi:[1,0] neg_lo:[0,1] neg_hi:[0,1]
	v_pk_add_f32 v[86:87], v[86:87], v[32:33] op_sel_hi:[1,0] neg_lo:[0,1] neg_hi:[0,1]
	v_pk_add_f32 v[102:103], v[102:103], v[32:33] op_sel_hi:[1,0] neg_lo:[0,1] neg_hi:[0,1]
	v_pk_add_f32 v[88:89], v[88:89], v[32:33] op_sel_hi:[1,0] neg_lo:[0,1] neg_hi:[0,1]
	v_pk_add_f32 v[104:105], v[104:105], v[32:33] op_sel_hi:[1,0] neg_lo:[0,1] neg_hi:[0,1]
	v_pk_add_f32 v[90:91], v[90:91], v[32:33] op_sel_hi:[1,0] neg_lo:[0,1] neg_hi:[0,1]
	v_pk_add_f32 v[106:107], v[106:107], v[32:33] op_sel_hi:[1,0] neg_lo:[0,1] neg_hi:[0,1]
	v_pk_add_f32 v[92:93], v[92:93], v[32:33] op_sel_hi:[1,0] neg_lo:[0,1] neg_hi:[0,1]
	v_pk_add_f32 v[108:109], v[108:109], v[32:33] op_sel_hi:[1,0] neg_lo:[0,1] neg_hi:[0,1]
	v_pk_add_f32 v[94:95], v[94:95], v[32:33] op_sel_hi:[1,0] neg_lo:[0,1] neg_hi:[0,1]
	v_pk_add_f32 v[110:111], v[110:111], v[32:33] op_sel_hi:[1,0] neg_lo:[0,1] neg_hi:[0,1]
	v_pk_mul_f32 v[14:15], v[14:15], v[34:35] op_sel_hi:[1,0]
	v_pk_mul_f32 v[12:13], v[12:13], v[34:35] op_sel_hi:[1,0]
	v_pk_mul_f32 v[10:11], v[10:11], v[34:35] op_sel_hi:[1,0]
	v_pk_mul_f32 v[8:9], v[8:9], v[34:35] op_sel_hi:[1,0]
	v_pk_mul_f32 v[6:7], v[6:7], v[34:35] op_sel_hi:[1,0]
	v_pk_mul_f32 v[4:5], v[4:5], v[34:35] op_sel_hi:[1,0]
	v_pk_mul_f32 v[2:3], v[2:3], v[34:35] op_sel_hi:[1,0]
	v_pk_mul_f32 v[0:1], v[0:1], v[34:35] op_sel_hi:[1,0]
	v_pk_mul_f32 v[30:31], v[30:31], v[34:35] op_sel_hi:[1,0]
	v_pk_mul_f32 v[28:29], v[28:29], v[34:35] op_sel_hi:[1,0]
	v_pk_mul_f32 v[26:27], v[26:27], v[34:35] op_sel_hi:[1,0]
	v_pk_mul_f32 v[24:25], v[24:25], v[34:35] op_sel_hi:[1,0]
	v_pk_mul_f32 v[22:23], v[22:23], v[34:35] op_sel_hi:[1,0]
	v_pk_mul_f32 v[20:21], v[20:21], v[34:35] op_sel_hi:[1,0]
	v_pk_mul_f32 v[18:19], v[18:19], v[34:35] op_sel_hi:[1,0]
	v_pk_mul_f32 v[16:17], v[16:17], v[34:35] op_sel_hi:[1,0]
	v_mul_f32_e32 v234, v234, v34
	v_mov_b32_e32 v49, v48
	v_mov_b32_e32 v50, v48
	v_mov_b32_e32 v51, v48
	v_mov_b32_e32 v32, v48
	v_mov_b32_e32 v33, v48
	v_mov_b32_e32 v34, v48
	v_mov_b32_e32 v35, v48
	v_mov_b32_e32 v36, v48
	v_mov_b32_e32 v37, v48
	v_mov_b32_e32 v38, v48
	v_mov_b32_e32 v39, v48
	v_mov_b32_e32 v40, v48
	v_mov_b32_e32 v41, v48
	v_mov_b32_e32 v42, v48
	v_mov_b32_e32 v43, v48
	v_mov_b32_e32 v44, v48
	v_mov_b32_e32 v45, v48
	v_mov_b32_e32 v46, v48
	v_mov_b32_e32 v47, v48
.LBB0_734:
	s_and_b32 s25, s17, 2
	s_mul_i32 s26, s25, 0x3400
	v_add_u32_e32 v64, s26, v227
	ds_read_b128 v[164:167], v64
	ds_read_b128 v[168:171], v64 offset:32
	ds_read_b128 v[172:175], v64 offset:6656
	ds_read_b128 v[176:179], v64 offset:6688
	ds_read_b128 v[180:183], v64 offset:64
	ds_read_b128 v[184:187], v64 offset:96
	ds_read_b128 v[188:191], v64 offset:6720
	ds_read_b128 v[192:195], v64 offset:6752
	ds_read_b128 v[236:239], v64 offset:128
	ds_read_b128 v[240:243], v64 offset:160
	ds_read_b128 v[244:247], v64 offset:6784
	ds_read_b128 v[160:163], v64 offset:6816
	s_mulk_i32 s24, 0x3000
	v_add_u32_e32 v253, s24, v232
	s_waitcnt lgkmcnt(11)
	v_mfma_f32_32x32x16_bf16 v[64:79], v[164:167], v[112:115], v[32:47]
	v_exp_f32_e32 v80, v80
	v_exp_f32_e32 v96, v96
	v_exp_f32_e32 v81, v81
	v_exp_f32_e32 v97, v97
	v_exp_f32_e32 v82, v82
	v_exp_f32_e32 v98, v98
	v_exp_f32_e32 v83, v83
	v_add_f32_e32 v164, v82, v80
	v_add_f32_e32 v165, v98, v96
	v_add_f32_e32 v166, v83, v81
	s_waitcnt lgkmcnt(10)
	v_mfma_f32_32x32x16_bf16 v[64:79], v[168:171], v[116:119], v[64:79]
	ds_read_b64_tr_b16 v[52:53], v253 offset:53248
	ds_read_b64_tr_b16 v[54:55], v253 offset:54784
	ds_read_b64_tr_b16 v[56:57], v253 offset:53312
	ds_read_b64_tr_b16 v[58:59], v253 offset:54848
	ds_read_b64_tr_b16 v[60:61], v253 offset:56320
	ds_read_b64_tr_b16 v[62:63], v253 offset:57856
	v_exp_f32_e32 v99, v99
	v_exp_f32_e32 v84, v84
	v_exp_f32_e32 v100, v100
	v_exp_f32_e32 v85, v85
	v_exp_f32_e32 v101, v101
	v_exp_f32_e32 v86, v86
	v_exp_f32_e32 v102, v102
	v_add_f32_e32 v167, v99, v97
	v_add_f32_e32 v164, v84, v164
	v_add_f32_e32 v165, v100, v165
	v_exp_f32_e32 v87, v87
	v_add_f32_e32 v166, v85, v166
	v_add_f32_e32 v167, v101, v167
	v_add_f32_e32 v164, v86, v164
	v_add_f32_e32 v165, v102, v165
	s_waitcnt lgkmcnt(13)
	v_mfma_f32_32x32x16_bf16 v[64:79], v[180:183], v[120:123], v[64:79]
	v_exp_f32_e32 v168, v88
	v_exp_f32_e32 v169, v89
	v_exp_f32_e32 v103, v103
	v_add_f32_e32 v166, v87, v166
	v_exp_f32_e32 v104, v104
	v_exp_f32_e32 v105, v105
	v_add_f32_e32 v88, v168, v164
	v_add_f32_e32 v164, v169, v166
	v_exp_f32_e32 v166, v90
	v_add_f32_e32 v167, v103, v167
	v_add_f32_e32 v89, v104, v165
	v_add_f32_e32 v165, v105, v167
	v_exp_f32_e32 v167, v91
	v_exp_f32_e32 v107, v107
	v_add_f32_e32 v88, v166, v88
	s_waitcnt lgkmcnt(12)
	v_mfma_f32_32x32x16_bf16 v[64:79], v[184:187], v[124:127], v[64:79]
	v_exp_f32_e32 v106, v106
	v_add_f32_e32 v90, v167, v164
	v_add_f32_e32 v91, v107, v165
	v_exp_f32_e32 v164, v92
	v_exp_f32_e32 v108, v108
	v_exp_f32_e32 v165, v93
	v_exp_f32_e32 v109, v109
	v_add_f32_e32 v89, v106, v89
	v_add_f32_e32 v88, v164, v88
	v_add_f32_e32 v89, v108, v89
	v_add_f32_e32 v90, v165, v90
	v_add_f32_e32 v91, v109, v91
	s_waitcnt lgkmcnt(9)
	v_mfma_f32_32x32x16_bf16 v[64:79], v[236:239], v[128:131], v[64:79]
	v_exp_f32_e32 v170, v94
	v_exp_f32_e32 v110, v110
	v_exp_f32_e32 v95, v95
	v_exp_f32_e32 v111, v111
	v_add_f32_e32 v88, v170, v88
	v_add_f32_e32 v89, v110, v89
	v_add_f32_e32 v90, v95, v90
	v_add_f32_e32 v91, v111, v91
	v_add_f32_e32 v88, v89, v88
	v_add_f32_e32 v89, v91, v90
	v_add_f32_e32 v171, v88, v89
	s_waitcnt lgkmcnt(8)
	v_mfma_f32_32x32x16_bf16 v[64:79], v[240:243], v[132:135], v[64:79]
	v_cvt_pk_bf16_f32 v88, v80, v81
	v_cvt_pk_bf16_f32 v89, v82, v83
	v_cvt_pk_bf16_f32 v90, v84, v85
	v_cvt_pk_bf16_f32 v91, v86, v87
	v_cvt_pk_bf16_f32 v80, v96, v97
	v_cvt_pk_bf16_f32 v81, v98, v99
	v_cvt_pk_bf16_f32 v82, v100, v101
	v_cvt_pk_bf16_f32 v83, v102, v103
	v_cvt_pk_bf16_f32 v84, v104, v105
	v_cvt_pk_bf16_f32 v85, v106, v107
	v_cvt_pk_bf16_f32 v86, v108, v109
	v_cvt_pk_bf16_f32 v87, v110, v111
	v_mfma_f32_32x32x16_bf16 v[96:111], v[172:175], v[112:115], v[32:47]
	v_cvt_pk_bf16_f32 v92, v168, v169
	v_cvt_pk_bf16_f32 v93, v166, v167
	v_cvt_pk_bf16_f32 v94, v164, v165
	v_cvt_pk_bf16_f32 v95, v170, v95
	v_mfma_f32_32x32x16_bf16 v[96:111], v[176:179], v[116:119], v[96:111]
	v_add_f32_e32 v234, v234, v171
	v_mfma_f32_32x32x16_bf16 v[96:111], v[188:191], v[120:123], v[96:111]
	v_mfma_f32_32x32x16_bf16 v[96:111], v[192:195], v[124:127], v[96:111]
	s_waitcnt lgkmcnt(7)
	v_mfma_f32_32x32x16_bf16 v[96:111], v[244:247], v[128:131], v[96:111]
	s_waitcnt lgkmcnt(6)
	v_mfma_f32_32x32x16_bf16 v[96:111], v[160:163], v[132:135], v[96:111]
	ds_read_b64_tr_b16 v[182:183], v253 offset:57920
	ds_read_b64_tr_b16 v[180:181], v253 offset:56384
	ds_read_b64_tr_b16 v[176:177], v253 offset:59392
	ds_read_b64_tr_b16 v[178:179], v253 offset:60928
	ds_read_b64_tr_b16 v[174:175], v253 offset:60992
	ds_read_b64_tr_b16 v[172:173], v253 offset:59456
	ds_read_b64_tr_b16 v[168:169], v253 offset:62464
	ds_read_b64_tr_b16 v[170:171], v253 offset:64000
	ds_read_b64_tr_b16 v[166:167], v253 offset:64064
	ds_read_b64_tr_b16 v[164:165], v253 offset:62528
	s_cmp_lt_u32 s17, s7
	s_cbranch_scc1 .LBB0_736
	v_add_u32_e32 v49, 0x60, v233
	v_add_u32_e32 v48, 64, v233
	v_cmp_le_i32_e32 vcc, v49, v229
	s_nop 7
	v_cndmask_b32_e32 v96, v224, v96, vcc
	v_cmp_lt_i32_e32 vcc, v48, v229
	s_nop 1
	v_cndmask_b32_e32 v65, v224, v65, vcc
	v_cmp_le_i32_e32 vcc, v48, v229
	v_add_u32_e32 v48, 0x61, v233
	s_nop 0
	v_cndmask_b32_e32 v64, v224, v64, vcc
	v_cmp_le_i32_e32 vcc, v48, v229
	v_add_u32_e32 v48, 0x42, v233
	s_nop 0
	v_cndmask_b32_e32 v97, v224, v97, vcc
	v_cmp_le_i32_e32 vcc, v48, v229
	v_add_u32_e32 v48, 0x62, v233
	s_nop 0
	v_cndmask_b32_e32 v66, v224, v66, vcc
	v_cmp_le_i32_e32 vcc, v48, v229
	v_add_u32_e32 v48, 0x43, v233
	s_nop 0
	v_cndmask_b32_e32 v98, v224, v98, vcc
	v_cmp_le_i32_e32 vcc, v48, v229
	v_add_u32_e32 v48, 0x63, v233
	s_nop 0
	v_cndmask_b32_e32 v67, v224, v67, vcc
	v_cmp_le_i32_e32 vcc, v48, v229
	v_add_u32_e32 v48, 0x48, v233
	s_nop 0
	v_cndmask_b32_e32 v99, v224, v99, vcc
	v_cmp_le_i32_e32 vcc, v48, v229
	v_add_u32_e32 v48, 0x68, v233
	s_nop 0
	v_cndmask_b32_e32 v68, v224, v68, vcc
	v_cmp_le_i32_e32 vcc, v48, v229
	v_add_u32_e32 v48, 0x49, v233
	s_nop 0
	v_cndmask_b32_e32 v100, v224, v100, vcc
	v_cmp_le_i32_e32 vcc, v48, v229
	v_add_u32_e32 v48, 0x69, v233
	s_nop 0
	v_cndmask_b32_e32 v69, v224, v69, vcc
	v_cmp_le_i32_e32 vcc, v48, v229
	v_add_u32_e32 v48, 0x4a, v233
	s_nop 0
	v_cndmask_b32_e32 v101, v224, v101, vcc
	v_cmp_le_i32_e32 vcc, v48, v229
	v_add_u32_e32 v48, 0x6a, v233
	s_nop 0
	v_cndmask_b32_e32 v70, v224, v70, vcc
	v_cmp_le_i32_e32 vcc, v48, v229
	v_add_u32_e32 v48, 0x4b, v233
	s_nop 0
	v_cndmask_b32_e32 v102, v224, v102, vcc
	v_cmp_le_i32_e32 vcc, v48, v229
	v_add_u32_e32 v48, 0x6b, v233
	s_nop 0
	v_cndmask_b32_e32 v71, v224, v71, vcc
	v_cmp_le_i32_e32 vcc, v48, v229
	v_add_u32_e32 v48, 0x50, v233
	s_nop 0
	v_cndmask_b32_e32 v103, v224, v103, vcc
	v_cmp_le_i32_e32 vcc, v48, v229
	v_add_u32_e32 v48, 0x70, v233
	s_nop 0
	v_cndmask_b32_e32 v72, v224, v72, vcc
	v_cmp_le_i32_e32 vcc, v48, v229
	v_add_u32_e32 v48, 0x51, v233
	s_nop 0
	v_cndmask_b32_e32 v104, v224, v104, vcc
	v_cmp_le_i32_e32 vcc, v48, v229
	v_add_u32_e32 v48, 0x71, v233
	s_nop 0
	v_cndmask_b32_e32 v73, v224, v73, vcc
	v_cmp_le_i32_e32 vcc, v48, v229
	v_add_u32_e32 v48, 0x52, v233
	s_nop 0
	v_cndmask_b32_e32 v105, v224, v105, vcc
	v_cmp_le_i32_e32 vcc, v48, v229
	v_add_u32_e32 v48, 0x72, v233
	s_nop 0
	v_cndmask_b32_e32 v74, v224, v74, vcc
	v_cmp_le_i32_e32 vcc, v48, v229
	v_add_u32_e32 v48, 0x53, v233
	s_nop 0
	v_cndmask_b32_e32 v106, v224, v106, vcc
	v_cmp_le_i32_e32 vcc, v48, v229
	v_add_u32_e32 v48, 0x73, v233
	s_nop 0
	v_cndmask_b32_e32 v75, v224, v75, vcc
	v_cmp_le_i32_e32 vcc, v48, v229
	v_add_u32_e32 v48, 0x58, v233
	s_nop 0
	v_cndmask_b32_e32 v107, v224, v107, vcc
	v_cmp_le_i32_e32 vcc, v48, v229
	v_add_u32_e32 v48, 0x78, v233
	s_nop 0
	v_cndmask_b32_e32 v76, v224, v76, vcc
	v_cmp_le_i32_e32 vcc, v48, v229
	v_add_u32_e32 v48, 0x59, v233
	s_nop 0
	v_cndmask_b32_e32 v108, v224, v108, vcc
	v_cmp_le_i32_e32 vcc, v48, v229
	v_add_u32_e32 v48, 0x79, v233
	s_nop 0
	v_cndmask_b32_e32 v77, v224, v77, vcc
	v_cmp_le_i32_e32 vcc, v48, v229
	v_add_u32_e32 v48, 0x5a, v233
	s_nop 0
	v_cndmask_b32_e32 v109, v224, v109, vcc
	v_cmp_le_i32_e32 vcc, v48, v229
	v_add_u32_e32 v48, 0x7a, v233
	s_nop 0
	v_cndmask_b32_e32 v78, v224, v78, vcc
	v_cmp_le_i32_e32 vcc, v48, v229
	v_add_u32_e32 v48, 0x5b, v233
	s_nop 0
	v_cndmask_b32_e32 v110, v224, v110, vcc
	v_cmp_le_i32_e32 vcc, v48, v229
	v_add_u32_e32 v48, 0x7b, v233
	s_nop 0
	v_cndmask_b32_e32 v79, v224, v79, vcc
	v_cmp_le_i32_e32 vcc, v48, v229
	s_nop 1
	v_cndmask_b32_e32 v111, v224, v111, vcc
.LBB0_736:
	s_waitcnt lgkmcnt(14)
	v_mfma_f32_32x32x16_bf16 v[0:15], v[52:55], v[88:91], v[0:15]
	v_max_f32_e32 v48, v65, v65
	v_max_f32_e32 v49, v64, v64
	v_max_f32_e32 v48, v49, v48
	s_waitcnt lgkmcnt(12)
	v_mfma_f32_32x32x16_bf16 v[16:31], v[56:59], v[88:91], v[16:31]
	s_nop 4
	v_max3_f32 v49, v66, v67, v97
	v_max3_f32 v48, v48, v96, v98
	v_max3_f32 v48, v48, v99, v68
	s_waitcnt lgkmcnt(10)
	v_mfma_f32_32x32x16_bf16 v[0:15], v[60:63], v[92:95], v[0:15]
	v_max3_f32 v49, v49, v70, v71
	v_max3_f32 v48, v48, v69, v100
	v_max3_f32 v49, v49, v102, v103
	s_waitcnt lgkmcnt(8)
	v_mfma_f32_32x32x16_bf16 v[16:31], v[180:183], v[92:95], v[16:31]
	v_max3_f32 v48, v48, v101, v72
	v_max3_f32 v49, v49, v74, v75
	v_max3_f32 v48, v48, v73, v104
	s_waitcnt lgkmcnt(6)
	v_mfma_f32_32x32x16_bf16 v[0:15], v[176:179], v[80:83], v[0:15]
	v_max3_f32 v49, v49, v106, v107
	v_max3_f32 v48, v48, v105, v76
	v_max3_f32 v49, v49, v78, v79
	s_waitcnt lgkmcnt(4)
	v_mfma_f32_32x32x16_bf16 v[16:31], v[172:175], v[80:83], v[16:31]
	v_max3_f32 v48, v48, v77, v108
	v_max3_f32 v49, v49, v110, v111
	v_max3_f32 v48, v48, v109, v49
	s_waitcnt lgkmcnt(2)
	v_mfma_f32_32x32x16_bf16 v[0:15], v[168:171], v[84:87], v[0:15]
	v_mov_b32_e32 v49, v48
	s_nop 1
	v_permlane32_swap_b32_e32 v48, v49
	s_waitcnt lgkmcnt(0)
	v_mfma_f32_32x32x16_bf16 v[16:31], v[164:167], v[84:87], v[16:31]
	s_andn2_b64 vcc, exec, s[8:9]
	s_cbranch_vccnz .LBB0_744
	s_and_b32 s22, s22, 3
	s_mul_i32 s8, s22, 0x3400
	s_add_i32 s24, s8, 0
	v_add_u32_e32 v50, s24, v225
	s_waitcnt vmcnt(1)
	ds_write_b128 v50, v[140:143]
	s_and_saveexec_b64 s[8:9], s[42:43]
	v_add_u32_e32 v50, s24, v226
	ds_write_b128 v50, v[136:139]
	s_or_b64 exec, exec, s[8:9]
	s_mulk_i32 s22, 0x3000
	v_add_u32_e32 v50, s22, v231
	s_waitcnt vmcnt(0)
	ds_write_b128 v50, v[156:159] offset:53248
	s_andn2_b64 vcc, exec, s[18:19]
	s_cbranch_vccz .LBB0_745

.LBB0_774:
	v_cmp_lt_f32_e32 vcc, s99, v48
	s_cbranch_vccz .LBB0_776
	v_max_f32_e32 v32, v48, v48
	v_max_f32_e32 v33, 0, v32
	v_exp_f32_e64 v32, -v33
	v_add_f32_e32 v230, v230, v33
	v_xor_b32_e32 v48, 0x80000000, v230
	v_sub_f32_e32 v79, v79, v33
	v_sub_f32_e32 v78, v78, v33
	v_sub_f32_e32 v77, v77, v33
	v_sub_f32_e32 v76, v76, v33
	v_sub_f32_e32 v75, v75, v33
	v_sub_f32_e32 v74, v74, v33
	v_sub_f32_e32 v73, v73, v33
	v_sub_f32_e32 v72, v72, v33
	v_sub_f32_e32 v71, v71, v33
	v_sub_f32_e32 v70, v70, v33
	v_sub_f32_e32 v69, v69, v33
	v_sub_f32_e32 v68, v68, v33
	v_sub_f32_e32 v67, v67, v33
	v_sub_f32_e32 v66, v66, v33
	v_sub_f32_e32 v65, v65, v33
	v_sub_f32_e32 v64, v64, v33
	v_sub_f32_e32 v111, v111, v33
	v_sub_f32_e32 v110, v110, v33
	v_sub_f32_e32 v109, v109, v33
	v_sub_f32_e32 v108, v108, v33
	v_sub_f32_e32 v107, v107, v33
	v_sub_f32_e32 v106, v106, v33
	v_sub_f32_e32 v105, v105, v33
	v_sub_f32_e32 v104, v104, v33
	v_sub_f32_e32 v103, v103, v33
	v_sub_f32_e32 v102, v102, v33
	v_sub_f32_e32 v101, v101, v33
	v_sub_f32_e32 v100, v100, v33
	v_sub_f32_e32 v99, v99, v33
	v_sub_f32_e32 v98, v98, v33
	v_sub_f32_e32 v97, v97, v33
	v_sub_f32_e32 v96, v96, v33
	v_pk_mul_f32 v[14:15], v[32:33], v[14:15] op_sel_hi:[0,1]
	v_pk_mul_f32 v[12:13], v[32:33], v[12:13] op_sel_hi:[0,1]
	v_pk_mul_f32 v[10:11], v[32:33], v[10:11] op_sel_hi:[0,1]
	v_pk_mul_f32 v[8:9], v[32:33], v[8:9] op_sel_hi:[0,1]
	v_pk_mul_f32 v[6:7], v[32:33], v[6:7] op_sel_hi:[0,1]
	v_pk_mul_f32 v[4:5], v[32:33], v[4:5] op_sel_hi:[0,1]
	v_pk_mul_f32 v[2:3], v[32:33], v[2:3] op_sel_hi:[0,1]
	v_pk_mul_f32 v[0:1], v[32:33], v[0:1] op_sel_hi:[0,1]
	v_pk_mul_f32 v[30:31], v[32:33], v[30:31] op_sel_hi:[0,1]
	v_pk_mul_f32 v[28:29], v[32:33], v[28:29] op_sel_hi:[0,1]
	v_pk_mul_f32 v[26:27], v[32:33], v[26:27] op_sel_hi:[0,1]
	v_pk_mul_f32 v[24:25], v[32:33], v[24:25] op_sel_hi:[0,1]
	v_pk_mul_f32 v[22:23], v[32:33], v[22:23] op_sel_hi:[0,1]
	v_pk_mul_f32 v[20:21], v[32:33], v[20:21] op_sel_hi:[0,1]
	v_pk_mul_f32 v[18:19], v[32:33], v[18:19] op_sel_hi:[0,1]
	v_pk_mul_f32 v[16:17], v[32:33], v[16:17] op_sel_hi:[0,1]
	v_mul_f32_e32 v233, v233, v32
	v_mov_b32_e32 v49, v48
	v_mov_b32_e32 v50, v48
	v_mov_b32_e32 v51, v48
	v_mov_b32_e32 v32, v48
	v_mov_b32_e32 v33, v48
	v_mov_b32_e32 v34, v48
	v_mov_b32_e32 v35, v48
	v_mov_b32_e32 v36, v48
	v_mov_b32_e32 v37, v48
	v_mov_b32_e32 v38, v48
	v_mov_b32_e32 v39, v48
	v_mov_b32_e32 v40, v48
	v_mov_b32_e32 v41, v48
	v_mov_b32_e32 v42, v48
	v_mov_b32_e32 v43, v48
	v_mov_b32_e32 v44, v48
	v_mov_b32_e32 v45, v48
	v_mov_b32_e32 v46, v48
	v_mov_b32_e32 v47, v48
	s_branch .LBB0_777
.LBB0_776:
.LBB0_777:
	s_add_i32 s22, s15, 1
	s_and_b32 s17, s22, 3
	s_mul_i32 s23, s17, 0x3400
	v_add_u32_e32 v80, s23, v228
	ds_read_b128 v[164:167], v80
	ds_read_b128 v[168:171], v80 offset:32
	ds_read_b128 v[172:175], v80 offset:6656
	ds_read_b128 v[176:179], v80 offset:6688
	ds_read_b128 v[180:183], v80 offset:64
	ds_read_b128 v[184:187], v80 offset:96
	ds_read_b128 v[188:191], v80 offset:6720
	ds_read_b128 v[192:195], v80 offset:6752
	ds_read_b128 v[234:237], v80 offset:128
	ds_read_b128 v[238:241], v80 offset:160
	ds_read_b128 v[242:245], v80 offset:6784
	ds_read_b128 v[160:163], v80 offset:6816
	s_and_b32 s15, s15, 2
	s_mul_i32 s23, s15, 0x3000
	v_add_u32_e32 v253, s23, v231
	s_waitcnt lgkmcnt(11)
	v_mfma_f32_32x32x16_bf16 v[80:95], v[164:167], v[112:115], v[32:47]
	v_exp_f32_e32 v64, v64
	v_exp_f32_e32 v66, v66
	v_exp_f32_e32 v68, v68
	v_exp_f32_e32 v164, v96
	v_exp_f32_e32 v65, v65
	v_exp_f32_e32 v165, v97
	v_exp_f32_e32 v70, v70
	v_add_f32_e32 v96, v66, v64
	v_exp_f32_e32 v67, v67
	v_add_f32_e32 v96, v68, v96
	v_add_f32_e32 v96, v70, v96
	s_waitcnt lgkmcnt(10)
	v_mfma_f32_32x32x16_bf16 v[80:95], v[168:171], v[116:119], v[80:95]
	ds_read_b64_tr_b16 v[52:53], v253 offset:53248
	ds_read_b64_tr_b16 v[54:55], v253 offset:54784
	ds_read_b64_tr_b16 v[56:57], v253 offset:53312
	ds_read_b64_tr_b16 v[58:59], v253 offset:54848
	ds_read_b64_tr_b16 v[60:61], v253 offset:56320
	ds_read_b64_tr_b16 v[62:63], v253 offset:57856
	v_exp_f32_e32 v169, v99
	v_exp_f32_e32 v168, v98
	v_add_f32_e32 v98, v67, v65
	v_exp_f32_e32 v166, v100
	v_add_f32_e32 v99, v169, v165
	v_exp_f32_e32 v69, v69
	v_exp_f32_e32 v167, v101
	v_exp_f32_e32 v170, v102
	v_add_f32_e32 v97, v168, v164
	v_add_f32_e32 v97, v166, v97
	v_add_f32_e32 v98, v69, v98
	v_add_f32_e32 v99, v167, v99
	v_add_f32_e32 v97, v170, v97
	s_waitcnt lgkmcnt(13)
	v_mfma_f32_32x32x16_bf16 v[80:95], v[180:183], v[120:123], v[80:95]
	v_exp_f32_e32 v71, v71
	v_exp_f32_e32 v171, v103
	v_exp_f32_e32 v180, v72
	v_exp_f32_e32 v181, v104
	v_exp_f32_e32 v182, v73
	v_exp_f32_e32 v183, v105
	v_add_f32_e32 v98, v71, v98
	v_add_f32_e32 v99, v171, v99
	v_add_f32_e32 v72, v180, v96
	v_add_f32_e32 v73, v181, v97
	v_add_f32_e32 v96, v182, v98
	v_add_f32_e32 v97, v183, v99
	s_waitcnt lgkmcnt(12)
	v_mfma_f32_32x32x16_bf16 v[80:95], v[184:187], v[124:127], v[80:95]
	v_exp_f32_e32 v184, v74
	v_exp_f32_e32 v185, v106
	v_exp_f32_e32 v186, v75
	v_exp_f32_e32 v187, v107
	v_add_f32_e32 v72, v184, v72
	v_add_f32_e32 v73, v185, v73
	v_add_f32_e32 v74, v186, v96
	v_add_f32_e32 v75, v187, v97
	s_waitcnt lgkmcnt(9)
	v_mfma_f32_32x32x16_bf16 v[80:95], v[234:237], v[128:131], v[80:95]
	v_exp_f32_e32 v236, v77
	v_exp_f32_e32 v234, v76
	v_exp_f32_e32 v235, v108
	v_exp_f32_e32 v237, v109
	v_exp_f32_e32 v79, v79
	v_add_f32_e32 v74, v236, v74
	v_add_f32_e32 v72, v234, v72
	v_add_f32_e32 v73, v235, v73
	v_add_f32_e32 v75, v237, v75
	v_add_f32_e32 v74, v79, v74
	v_cvt_pk_bf16_f32 v76, v180, v182
	v_cvt_pk_bf16_f32 v77, v184, v186
	s_waitcnt lgkmcnt(8)
	v_mfma_f32_32x32x16_bf16 v[80:95], v[238:241], v[132:135], v[80:95]
	v_exp_f32_e32 v238, v78
	v_exp_f32_e32 v239, v110
	v_exp_f32_e32 v240, v111
	v_add_f32_e32 v72, v238, v72
	v_add_f32_e32 v73, v239, v73
	v_add_f32_e32 v75, v240, v75
	v_add_f32_e32 v72, v73, v72
	v_add_f32_e32 v73, v75, v74
	v_cvt_pk_bf16_f32 v74, v68, v69
	v_cvt_pk_bf16_f32 v75, v70, v71
	v_mfma_f32_32x32x16_bf16 v[96:111], v[172:175], v[112:115], v[32:47]
	v_add_f32_e32 v172, v73, v72
	v_cvt_pk_bf16_f32 v72, v64, v65
	v_cvt_pk_bf16_f32 v73, v66, v67
	v_cvt_pk_bf16_f32 v64, v164, v165
	v_cvt_pk_bf16_f32 v65, v168, v169
	v_cvt_pk_bf16_f32 v66, v166, v167
	v_cvt_pk_bf16_f32 v67, v170, v171
	v_mfma_f32_32x32x16_bf16 v[96:111], v[176:179], v[116:119], v[96:111]
	v_cvt_pk_bf16_f32 v78, v234, v236
	v_cvt_pk_bf16_f32 v79, v238, v79
	v_cvt_pk_bf16_f32 v68, v181, v183
	v_cvt_pk_bf16_f32 v69, v185, v187
	v_cvt_pk_bf16_f32 v70, v235, v237
	v_cvt_pk_bf16_f32 v71, v239, v240
	v_add_f32_e32 v233, v233, v172
	v_mfma_f32_32x32x16_bf16 v[96:111], v[188:191], v[120:123], v[96:111]
	v_mfma_f32_32x32x16_bf16 v[96:111], v[192:195], v[124:127], v[96:111]
	s_waitcnt lgkmcnt(7)
	v_mfma_f32_32x32x16_bf16 v[96:111], v[242:245], v[128:131], v[96:111]
	s_waitcnt lgkmcnt(6)
	v_mfma_f32_32x32x16_bf16 v[96:111], v[160:163], v[132:135], v[96:111]
	ds_read_b64_tr_b16 v[182:183], v253 offset:57920
	ds_read_b64_tr_b16 v[180:181], v253 offset:56384
	ds_read_b64_tr_b16 v[176:177], v253 offset:59392
	ds_read_b64_tr_b16 v[178:179], v253 offset:60928
	ds_read_b64_tr_b16 v[174:175], v253 offset:60992
	ds_read_b64_tr_b16 v[172:173], v253 offset:59456
	ds_read_b64_tr_b16 v[168:169], v253 offset:62464
	ds_read_b64_tr_b16 v[170:171], v253 offset:64000
	ds_read_b64_tr_b16 v[166:167], v253 offset:64064
	ds_read_b64_tr_b16 v[164:165], v253 offset:62528
	s_cmp_lt_i32 s22, s2
	s_cbranch_scc1 .LBB0_779
	v_subrev_u32_e32 v160, 32, v232
	v_cmp_le_i32_e32 vcc, v232, v229
	s_nop 1
	v_cndmask_b32_e32 v96, v224, v96, vcc
	v_cmp_lt_i32_e32 vcc, v160, v229
	s_nop 1
	v_cndmask_b32_e32 v81, v224, v81, vcc
	v_cmp_le_i32_e32 vcc, v160, v229
	v_add_u32_e32 v160, 1, v232
	s_nop 0
	v_cndmask_b32_e32 v80, v224, v80, vcc
	v_cmp_le_i32_e32 vcc, v160, v229
	v_subrev_u32_e32 v160, 30, v232
	s_nop 0
	v_cndmask_b32_e32 v97, v224, v97, vcc
	v_cmp_le_i32_e32 vcc, v160, v229
	v_add_u32_e32 v160, 2, v232
	s_nop 0
	v_cndmask_b32_e32 v82, v224, v82, vcc
	v_cmp_le_i32_e32 vcc, v160, v229
	v_subrev_u32_e32 v160, 29, v232
	s_nop 0
	v_cndmask_b32_e32 v98, v224, v98, vcc
	v_cmp_le_i32_e32 vcc, v160, v229
	v_add_u32_e32 v160, 3, v232
	s_nop 0
	v_cndmask_b32_e32 v83, v224, v83, vcc
	v_cmp_le_i32_e32 vcc, v160, v229
	v_subrev_u32_e32 v160, 24, v232
	s_nop 0
	v_cndmask_b32_e32 v99, v224, v99, vcc
	v_cmp_le_i32_e32 vcc, v160, v229
	v_add_u32_e32 v160, 8, v232
	s_nop 0
	v_cndmask_b32_e32 v84, v224, v84, vcc
	v_cmp_le_i32_e32 vcc, v160, v229
	v_subrev_u32_e32 v160, 23, v232
	s_nop 0
	v_cndmask_b32_e32 v100, v224, v100, vcc
	v_cmp_le_i32_e32 vcc, v160, v229
	v_add_u32_e32 v160, 9, v232
	s_nop 0
	v_cndmask_b32_e32 v85, v224, v85, vcc
	v_cmp_le_i32_e32 vcc, v160, v229
	v_subrev_u32_e32 v160, 22, v232
	s_nop 0
	v_cndmask_b32_e32 v101, v224, v101, vcc
	v_cmp_le_i32_e32 vcc, v160, v229
	v_add_u32_e32 v160, 10, v232
	s_nop 0
	v_cndmask_b32_e32 v86, v224, v86, vcc
	v_cmp_le_i32_e32 vcc, v160, v229
	v_subrev_u32_e32 v160, 21, v232
	s_nop 0
	v_cndmask_b32_e32 v102, v224, v102, vcc
	v_cmp_le_i32_e32 vcc, v160, v229
	v_add_u32_e32 v160, 11, v232
	s_nop 0
	v_cndmask_b32_e32 v87, v224, v87, vcc
	v_cmp_le_i32_e32 vcc, v160, v229
	v_add_u32_e32 v160, -16, v232
	s_nop 0
	v_cndmask_b32_e32 v103, v224, v103, vcc
	v_cmp_le_i32_e32 vcc, v160, v229
	v_add_u32_e32 v160, 16, v232
	s_nop 0
	v_cndmask_b32_e32 v88, v224, v88, vcc
	v_cmp_le_i32_e32 vcc, v160, v229
	v_add_u32_e32 v160, -15, v232
	s_nop 0
	v_cndmask_b32_e32 v104, v224, v104, vcc
	v_cmp_le_i32_e32 vcc, v160, v229
	v_add_u32_e32 v160, 17, v232
	s_nop 0
	v_cndmask_b32_e32 v89, v224, v89, vcc
	v_cmp_le_i32_e32 vcc, v160, v229
	v_add_u32_e32 v160, -14, v232
	s_nop 0
	v_cndmask_b32_e32 v105, v224, v105, vcc
	v_cmp_le_i32_e32 vcc, v160, v229
	v_add_u32_e32 v160, 18, v232
	s_nop 0
	v_cndmask_b32_e32 v90, v224, v90, vcc
	v_cmp_le_i32_e32 vcc, v160, v229
	v_add_u32_e32 v160, -13, v232
	s_nop 0
	v_cndmask_b32_e32 v106, v224, v106, vcc
	v_cmp_le_i32_e32 vcc, v160, v229
	v_add_u32_e32 v160, 19, v232
	s_nop 0
	v_cndmask_b32_e32 v91, v224, v91, vcc
	v_cmp_le_i32_e32 vcc, v160, v229
	v_add_u32_e32 v160, -8, v232
	s_nop 0
	v_cndmask_b32_e32 v107, v224, v107, vcc
	v_cmp_le_i32_e32 vcc, v160, v229
	v_add_u32_e32 v160, 24, v232
	s_nop 0
	v_cndmask_b32_e32 v92, v224, v92, vcc
	v_cmp_le_i32_e32 vcc, v160, v229
	v_add_u32_e32 v160, -7, v232
	s_nop 0
	v_cndmask_b32_e32 v108, v224, v108, vcc
	v_cmp_le_i32_e32 vcc, v160, v229
	v_add_u32_e32 v160, 25, v232
	s_nop 0
	v_cndmask_b32_e32 v93, v224, v93, vcc
	v_cmp_le_i32_e32 vcc, v160, v229
	v_add_u32_e32 v160, -6, v232
	s_nop 0
	v_cndmask_b32_e32 v109, v224, v109, vcc
	v_cmp_le_i32_e32 vcc, v160, v229
	v_add_u32_e32 v160, 26, v232
	s_nop 0
	v_cndmask_b32_e32 v94, v224, v94, vcc
	v_cmp_le_i32_e32 vcc, v160, v229
	v_add_u32_e32 v160, -5, v232
	s_nop 0
	v_cndmask_b32_e32 v110, v224, v110, vcc
	v_cmp_le_i32_e32 vcc, v160, v229
	v_add_u32_e32 v160, 27, v232
	s_nop 0
	v_cndmask_b32_e32 v95, v224, v95, vcc
	v_cmp_le_i32_e32 vcc, v160, v229
	s_nop 1
	v_cndmask_b32_e32 v111, v224, v111, vcc
.LBB0_779:
	s_waitcnt lgkmcnt(14)
	v_mfma_f32_32x32x16_bf16 v[0:15], v[52:55], v[72:75], v[0:15]
	v_max_f32_e32 v160, v81, v81
	v_max_f32_e32 v161, v80, v80
	v_max_f32_e32 v160, v161, v160
	s_waitcnt lgkmcnt(12)
	v_mfma_f32_32x32x16_bf16 v[16:31], v[56:59], v[72:75], v[16:31]
	v_max3_f32 v72, v82, v83, v97
	v_max3_f32 v73, v160, v96, v98
	v_max3_f32 v73, v73, v99, v84
	s_waitcnt lgkmcnt(10)
	v_mfma_f32_32x32x16_bf16 v[0:15], v[60:63], v[76:79], v[0:15]
	v_max3_f32 v72, v72, v86, v87
	v_max3_f32 v73, v73, v85, v100
	v_max3_f32 v72, v72, v102, v103
	s_waitcnt lgkmcnt(8)
	v_mfma_f32_32x32x16_bf16 v[16:31], v[180:183], v[76:79], v[16:31]
	v_max3_f32 v73, v73, v101, v88
	v_max3_f32 v72, v72, v90, v91
	v_max3_f32 v73, v73, v89, v104
	s_waitcnt lgkmcnt(6)
	v_mfma_f32_32x32x16_bf16 v[0:15], v[176:179], v[64:67], v[0:15]
	v_max3_f32 v72, v72, v106, v107
	v_max3_f32 v73, v73, v105, v92
	v_max3_f32 v72, v72, v94, v95
	s_waitcnt lgkmcnt(4)
	v_mfma_f32_32x32x16_bf16 v[16:31], v[172:175], v[64:67], v[16:31]
	v_max3_f32 v64, v73, v93, v108
	v_max3_f32 v65, v72, v110, v111
	v_max3_f32 v64, v64, v109, v65
	s_waitcnt lgkmcnt(2)
	v_mfma_f32_32x32x16_bf16 v[0:15], v[168:171], v[68:71], v[0:15]
	v_mov_b32_e32 v65, v64
	s_nop 1
	v_permlane32_swap_b32_e32 v64, v65
	v_max_f32_e32 v65, v65, v65
	v_max_f32_e32 v64, v64, v64
	v_max_f32_e32 v64, v64, v65
	s_waitcnt lgkmcnt(0)
	v_mfma_f32_32x32x16_bf16 v[16:31], v[164:167], v[68:71], v[16:31]
	v_cmp_lt_f32_e32 vcc, s99, v64
	s_cbranch_vccz .LBB0_781
	v_max_f32_e32 v32, v64, v64
	v_max_f32_e32 v32, 0, v32
	v_exp_f32_e64 v34, -v32
	v_add_f32_e32 v230, v230, v32
	v_xor_b32_e32 v48, 0x80000000, v230
	v_pk_add_f32 v[80:81], v[80:81], v[32:33] op_sel_hi:[1,0] neg_lo:[0,1] neg_hi:[0,1]
	v_pk_add_f32 v[96:97], v[96:97], v[32:33] op_sel_hi:[1,0] neg_lo:[0,1] neg_hi:[0,1]
	v_pk_add_f32 v[82:83], v[82:83], v[32:33] op_sel_hi:[1,0] neg_lo:[0,1] neg_hi:[0,1]
	v_pk_add_f32 v[98:99], v[98:99], v[32:33] op_sel_hi:[1,0] neg_lo:[0,1] neg_hi:[0,1]
	v_pk_add_f32 v[84:85], v[84:85], v[32:33] op_sel_hi:[1,0] neg_lo:[0,1] neg_hi:[0,1]
	v_pk_add_f32 v[100:101], v[100:101], v[32:33] op_sel_hi:[1,0] neg_lo:[0,1] neg_hi:[0,1]
	v_pk_add_f32 v[86:87], v[86:87], v[32:33] op_sel_hi:[1,0] neg_lo:[0,1] neg_hi:[0,1]
	v_pk_add_f32 v[102:103], v[102:103], v[32:33] op_sel_hi:[1,0] neg_lo:[0,1] neg_hi:[0,1]
	v_pk_add_f32 v[88:89], v[88:89], v[32:33] op_sel_hi:[1,0] neg_lo:[0,1] neg_hi:[0,1]
	v_pk_add_f32 v[104:105], v[104:105], v[32:33] op_sel_hi:[1,0] neg_lo:[0,1] neg_hi:[0,1]
	v_pk_add_f32 v[90:91], v[90:91], v[32:33] op_sel_hi:[1,0] neg_lo:[0,1] neg_hi:[0,1]
	v_pk_add_f32 v[106:107], v[106:107], v[32:33] op_sel_hi:[1,0] neg_lo:[0,1] neg_hi:[0,1]
	v_pk_add_f32 v[92:93], v[92:93], v[32:33] op_sel_hi:[1,0] neg_lo:[0,1] neg_hi:[0,1]
	v_pk_add_f32 v[108:109], v[108:109], v[32:33] op_sel_hi:[1,0] neg_lo:[0,1] neg_hi:[0,1]
	v_pk_add_f32 v[94:95], v[94:95], v[32:33] op_sel_hi:[1,0] neg_lo:[0,1] neg_hi:[0,1]
	v_pk_add_f32 v[110:111], v[110:111], v[32:33] op_sel_hi:[1,0] neg_lo:[0,1] neg_hi:[0,1]
	v_pk_mul_f32 v[14:15], v[14:15], v[34:35] op_sel_hi:[1,0]
	v_pk_mul_f32 v[12:13], v[12:13], v[34:35] op_sel_hi:[1,0]
	v_pk_mul_f32 v[10:11], v[10:11], v[34:35] op_sel_hi:[1,0]
	v_pk_mul_f32 v[8:9], v[8:9], v[34:35] op_sel_hi:[1,0]
	v_pk_mul_f32 v[6:7], v[6:7], v[34:35] op_sel_hi:[1,0]
	v_pk_mul_f32 v[4:5], v[4:5], v[34:35] op_sel_hi:[1,0]
	v_pk_mul_f32 v[2:3], v[2:3], v[34:35] op_sel_hi:[1,0]
	v_pk_mul_f32 v[0:1], v[0:1], v[34:35] op_sel_hi:[1,0]
	v_pk_mul_f32 v[30:31], v[30:31], v[34:35] op_sel_hi:[1,0]
	v_pk_mul_f32 v[28:29], v[28:29], v[34:35] op_sel_hi:[1,0]
	v_pk_mul_f32 v[26:27], v[26:27], v[34:35] op_sel_hi:[1,0]
	v_pk_mul_f32 v[24:25], v[24:25], v[34:35] op_sel_hi:[1,0]
	v_pk_mul_f32 v[22:23], v[22:23], v[34:35] op_sel_hi:[1,0]
	v_pk_mul_f32 v[20:21], v[20:21], v[34:35] op_sel_hi:[1,0]
	v_pk_mul_f32 v[18:19], v[18:19], v[34:35] op_sel_hi:[1,0]
	v_pk_mul_f32 v[16:17], v[16:17], v[34:35] op_sel_hi:[1,0]
	v_mul_f32_e32 v233, v233, v34
	v_mov_b32_e32 v49, v48
	v_mov_b32_e32 v50, v48
	v_mov_b32_e32 v51, v48
	v_mov_b32_e32 v32, v48
	v_mov_b32_e32 v33, v48
	v_mov_b32_e32 v34, v48
	v_mov_b32_e32 v35, v48
	v_mov_b32_e32 v36, v48
	v_mov_b32_e32 v37, v48
	v_mov_b32_e32 v38, v48
	v_mov_b32_e32 v39, v48
	v_mov_b32_e32 v40, v48
	v_mov_b32_e32 v41, v48
	v_mov_b32_e32 v42, v48
	v_mov_b32_e32 v43, v48
	v_mov_b32_e32 v44, v48
	v_mov_b32_e32 v45, v48
	v_mov_b32_e32 v46, v48
	v_mov_b32_e32 v47, v48
.LBB0_781:
	s_and_b32 s22, s11, 2
	s_mul_i32 s23, s22, 0x3400
	v_add_u32_e32 v64, s23, v228
	ds_read_b128 v[164:167], v64
	ds_read_b128 v[168:171], v64 offset:32
	ds_read_b128 v[172:175], v64 offset:6656
	ds_read_b128 v[176:179], v64 offset:6688
	ds_read_b128 v[180:183], v64 offset:64
	ds_read_b128 v[184:187], v64 offset:96
	ds_read_b128 v[188:191], v64 offset:6720
	ds_read_b128 v[192:195], v64 offset:6752
	ds_read_b128 v[234:237], v64 offset:128
	ds_read_b128 v[238:241], v64 offset:160
	ds_read_b128 v[242:245], v64 offset:6784
	ds_read_b128 v[160:163], v64 offset:6816
	s_mulk_i32 s17, 0x3000
	v_add_u32_e32 v253, s17, v231
	s_waitcnt lgkmcnt(11)
	v_mfma_f32_32x32x16_bf16 v[64:79], v[164:167], v[112:115], v[32:47]
	v_exp_f32_e32 v80, v80
	v_exp_f32_e32 v96, v96
	v_exp_f32_e32 v81, v81
	v_exp_f32_e32 v97, v97
	v_exp_f32_e32 v82, v82
	v_exp_f32_e32 v98, v98
	v_exp_f32_e32 v83, v83
	v_add_f32_e32 v164, v82, v80
	v_add_f32_e32 v165, v98, v96
	v_add_f32_e32 v166, v83, v81
	s_waitcnt lgkmcnt(10)
	v_mfma_f32_32x32x16_bf16 v[64:79], v[168:171], v[116:119], v[64:79]
	ds_read_b64_tr_b16 v[52:53], v253 offset:53248
	ds_read_b64_tr_b16 v[54:55], v253 offset:54784
	ds_read_b64_tr_b16 v[56:57], v253 offset:53312
	ds_read_b64_tr_b16 v[58:59], v253 offset:54848
	ds_read_b64_tr_b16 v[60:61], v253 offset:56320
	ds_read_b64_tr_b16 v[62:63], v253 offset:57856
	v_exp_f32_e32 v99, v99
	v_exp_f32_e32 v84, v84
	v_exp_f32_e32 v100, v100
	v_exp_f32_e32 v85, v85
	v_exp_f32_e32 v101, v101
	v_exp_f32_e32 v86, v86
	v_exp_f32_e32 v102, v102
	v_add_f32_e32 v167, v99, v97
	v_add_f32_e32 v164, v84, v164
	v_add_f32_e32 v165, v100, v165
	v_exp_f32_e32 v87, v87
	v_add_f32_e32 v166, v85, v166
	v_add_f32_e32 v167, v101, v167
	v_add_f32_e32 v164, v86, v164
	v_add_f32_e32 v165, v102, v165
	s_waitcnt lgkmcnt(13)
	v_mfma_f32_32x32x16_bf16 v[64:79], v[180:183], v[120:123], v[64:79]
	v_exp_f32_e32 v168, v88
	v_exp_f32_e32 v169, v89
	v_exp_f32_e32 v103, v103
	v_add_f32_e32 v166, v87, v166
	v_exp_f32_e32 v104, v104
	v_exp_f32_e32 v105, v105
	v_add_f32_e32 v88, v168, v164
	v_add_f32_e32 v164, v169, v166
	v_exp_f32_e32 v166, v90
	v_add_f32_e32 v167, v103, v167
	v_add_f32_e32 v89, v104, v165
	v_add_f32_e32 v165, v105, v167
	v_exp_f32_e32 v167, v91
	v_exp_f32_e32 v107, v107
	v_add_f32_e32 v88, v166, v88
	s_waitcnt lgkmcnt(12)
	v_mfma_f32_32x32x16_bf16 v[64:79], v[184:187], v[124:127], v[64:79]
	v_exp_f32_e32 v106, v106
	v_add_f32_e32 v90, v167, v164
	v_add_f32_e32 v91, v107, v165
	v_exp_f32_e32 v164, v92
	v_exp_f32_e32 v108, v108
	v_exp_f32_e32 v165, v93
	v_exp_f32_e32 v109, v109
	v_add_f32_e32 v89, v106, v89
	v_add_f32_e32 v88, v164, v88
	v_add_f32_e32 v89, v108, v89
	v_add_f32_e32 v90, v165, v90
	v_add_f32_e32 v91, v109, v91
	s_waitcnt lgkmcnt(9)
	v_mfma_f32_32x32x16_bf16 v[64:79], v[234:237], v[128:131], v[64:79]
	v_exp_f32_e32 v170, v94
	v_exp_f32_e32 v110, v110
	v_exp_f32_e32 v95, v95
	v_exp_f32_e32 v111, v111
	v_add_f32_e32 v88, v170, v88
	v_add_f32_e32 v89, v110, v89
	v_add_f32_e32 v90, v95, v90
	v_add_f32_e32 v91, v111, v91
	v_add_f32_e32 v88, v89, v88
	v_add_f32_e32 v89, v91, v90
	v_add_f32_e32 v171, v88, v89
	s_waitcnt lgkmcnt(8)
	v_mfma_f32_32x32x16_bf16 v[64:79], v[238:241], v[132:135], v[64:79]
	v_cvt_pk_bf16_f32 v88, v80, v81
	v_cvt_pk_bf16_f32 v89, v82, v83
	v_cvt_pk_bf16_f32 v90, v84, v85
	v_cvt_pk_bf16_f32 v91, v86, v87
	v_cvt_pk_bf16_f32 v80, v96, v97
	v_cvt_pk_bf16_f32 v81, v98, v99
	v_cvt_pk_bf16_f32 v82, v100, v101
	v_cvt_pk_bf16_f32 v83, v102, v103
	v_cvt_pk_bf16_f32 v84, v104, v105
	v_cvt_pk_bf16_f32 v85, v106, v107
	v_cvt_pk_bf16_f32 v86, v108, v109
	v_cvt_pk_bf16_f32 v87, v110, v111
	v_mfma_f32_32x32x16_bf16 v[96:111], v[172:175], v[112:115], v[32:47]
	v_cvt_pk_bf16_f32 v92, v168, v169
	v_cvt_pk_bf16_f32 v93, v166, v167
	v_cvt_pk_bf16_f32 v94, v164, v165
	v_cvt_pk_bf16_f32 v95, v170, v95
	v_mfma_f32_32x32x16_bf16 v[96:111], v[176:179], v[116:119], v[96:111]
	v_add_f32_e32 v233, v233, v171
	v_mfma_f32_32x32x16_bf16 v[96:111], v[188:191], v[120:123], v[96:111]
	v_mfma_f32_32x32x16_bf16 v[96:111], v[192:195], v[124:127], v[96:111]
	s_waitcnt lgkmcnt(7)
	v_mfma_f32_32x32x16_bf16 v[96:111], v[242:245], v[128:131], v[96:111]
	s_waitcnt lgkmcnt(6)
	v_mfma_f32_32x32x16_bf16 v[96:111], v[160:163], v[132:135], v[96:111]
	ds_read_b64_tr_b16 v[182:183], v253 offset:57920
	ds_read_b64_tr_b16 v[180:181], v253 offset:56384
	ds_read_b64_tr_b16 v[176:177], v253 offset:59392
	ds_read_b64_tr_b16 v[178:179], v253 offset:60928
	ds_read_b64_tr_b16 v[174:175], v253 offset:60992
	ds_read_b64_tr_b16 v[172:173], v253 offset:59456
	ds_read_b64_tr_b16 v[168:169], v253 offset:62464
	ds_read_b64_tr_b16 v[170:171], v253 offset:64000
	ds_read_b64_tr_b16 v[166:167], v253 offset:64064
	ds_read_b64_tr_b16 v[164:165], v253 offset:62528
	s_cmp_lt_i32 s11, s2
	s_cbranch_scc1 .LBB0_783
	v_add_u32_e32 v49, 64, v232
	v_add_u32_e32 v48, 32, v232
	v_cmp_le_i32_e32 vcc, v49, v229
	s_nop 7
	v_cndmask_b32_e32 v96, v224, v96, vcc
	v_cmp_lt_i32_e32 vcc, v48, v229
	s_nop 1
	v_cndmask_b32_e32 v65, v224, v65, vcc
	v_cmp_le_i32_e32 vcc, v48, v229
	v_add_u32_e32 v48, 0x41, v232
	s_nop 0
	v_cndmask_b32_e32 v64, v224, v64, vcc
	v_cmp_le_i32_e32 vcc, v48, v229
	v_add_u32_e32 v48, 34, v232
	s_nop 0
	v_cndmask_b32_e32 v97, v224, v97, vcc
	v_cmp_le_i32_e32 vcc, v48, v229
	v_add_u32_e32 v48, 0x42, v232
	s_nop 0
	v_cndmask_b32_e32 v66, v224, v66, vcc
	v_cmp_le_i32_e32 vcc, v48, v229
	v_add_u32_e32 v48, 35, v232
	s_nop 0
	v_cndmask_b32_e32 v98, v224, v98, vcc
	v_cmp_le_i32_e32 vcc, v48, v229
	v_add_u32_e32 v48, 0x43, v232
	s_nop 0
	v_cndmask_b32_e32 v67, v224, v67, vcc
	v_cmp_le_i32_e32 vcc, v48, v229
	v_add_u32_e32 v48, 40, v232
	s_nop 0
	v_cndmask_b32_e32 v99, v224, v99, vcc
	v_cmp_le_i32_e32 vcc, v48, v229
	v_add_u32_e32 v48, 0x48, v232
	s_nop 0
	v_cndmask_b32_e32 v68, v224, v68, vcc
	v_cmp_le_i32_e32 vcc, v48, v229
	v_add_u32_e32 v48, 41, v232
	s_nop 0
	v_cndmask_b32_e32 v100, v224, v100, vcc
	v_cmp_le_i32_e32 vcc, v48, v229
	v_add_u32_e32 v48, 0x49, v232
	s_nop 0
	v_cndmask_b32_e32 v69, v224, v69, vcc
	v_cmp_le_i32_e32 vcc, v48, v229
	v_add_u32_e32 v48, 42, v232
	s_nop 0
	v_cndmask_b32_e32 v101, v224, v101, vcc
	v_cmp_le_i32_e32 vcc, v48, v229
	v_add_u32_e32 v48, 0x4a, v232
	s_nop 0
	v_cndmask_b32_e32 v70, v224, v70, vcc
	v_cmp_le_i32_e32 vcc, v48, v229
	v_add_u32_e32 v48, 43, v232
	s_nop 0
	v_cndmask_b32_e32 v102, v224, v102, vcc
	v_cmp_le_i32_e32 vcc, v48, v229
	v_add_u32_e32 v48, 0x4b, v232
	s_nop 0
	v_cndmask_b32_e32 v71, v224, v71, vcc
	v_cmp_le_i32_e32 vcc, v48, v229
	v_add_u32_e32 v48, 48, v232
	s_nop 0
	v_cndmask_b32_e32 v103, v224, v103, vcc
	v_cmp_le_i32_e32 vcc, v48, v229
	v_add_u32_e32 v48, 0x50, v232
	s_nop 0
	v_cndmask_b32_e32 v72, v224, v72, vcc
	v_cmp_le_i32_e32 vcc, v48, v229
	v_add_u32_e32 v48, 49, v232
	s_nop 0
	v_cndmask_b32_e32 v104, v224, v104, vcc
	v_cmp_le_i32_e32 vcc, v48, v229
	v_add_u32_e32 v48, 0x51, v232
	s_nop 0
	v_cndmask_b32_e32 v73, v224, v73, vcc
	v_cmp_le_i32_e32 vcc, v48, v229
	v_add_u32_e32 v48, 50, v232
	s_nop 0
	v_cndmask_b32_e32 v105, v224, v105, vcc
	v_cmp_le_i32_e32 vcc, v48, v229
	v_add_u32_e32 v48, 0x52, v232
	s_nop 0
	v_cndmask_b32_e32 v74, v224, v74, vcc
	v_cmp_le_i32_e32 vcc, v48, v229
	v_add_u32_e32 v48, 51, v232
	s_nop 0
	v_cndmask_b32_e32 v106, v224, v106, vcc
	v_cmp_le_i32_e32 vcc, v48, v229
	v_add_u32_e32 v48, 0x53, v232
	s_nop 0
	v_cndmask_b32_e32 v75, v224, v75, vcc
	v_cmp_le_i32_e32 vcc, v48, v229
	v_add_u32_e32 v48, 56, v232
	s_nop 0
	v_cndmask_b32_e32 v107, v224, v107, vcc
	v_cmp_le_i32_e32 vcc, v48, v229
	v_add_u32_e32 v48, 0x58, v232
	s_nop 0
	v_cndmask_b32_e32 v76, v224, v76, vcc
	v_cmp_le_i32_e32 vcc, v48, v229
	v_add_u32_e32 v48, 57, v232
	s_nop 0
	v_cndmask_b32_e32 v108, v224, v108, vcc
	v_cmp_le_i32_e32 vcc, v48, v229
	v_add_u32_e32 v48, 0x59, v232
	s_nop 0
	v_cndmask_b32_e32 v77, v224, v77, vcc
	v_cmp_le_i32_e32 vcc, v48, v229
	v_add_u32_e32 v48, 58, v232
	s_nop 0
	v_cndmask_b32_e32 v109, v224, v109, vcc
	v_cmp_le_i32_e32 vcc, v48, v229
	v_add_u32_e32 v48, 0x5a, v232
	s_nop 0
	v_cndmask_b32_e32 v78, v224, v78, vcc
	v_cmp_le_i32_e32 vcc, v48, v229
	v_add_u32_e32 v48, 59, v232
	s_nop 0
	v_cndmask_b32_e32 v110, v224, v110, vcc
	v_cmp_le_i32_e32 vcc, v48, v229
	v_add_u32_e32 v48, 0x5b, v232
	s_nop 0
	v_cndmask_b32_e32 v79, v224, v79, vcc
	v_cmp_le_i32_e32 vcc, v48, v229
	s_nop 1
	v_cndmask_b32_e32 v111, v224, v111, vcc
.LBB0_783:
	s_waitcnt lgkmcnt(14)
	v_mfma_f32_32x32x16_bf16 v[0:15], v[52:55], v[88:91], v[0:15]
	v_max_f32_e32 v48, v65, v65
	v_max_f32_e32 v49, v64, v64
	v_max_f32_e32 v48, v49, v48
	s_waitcnt lgkmcnt(12)
	v_mfma_f32_32x32x16_bf16 v[16:31], v[56:59], v[88:91], v[16:31]
	s_nop 4
	v_max3_f32 v49, v66, v67, v97
	v_max3_f32 v48, v48, v96, v98
	v_max3_f32 v48, v48, v99, v68
	s_waitcnt lgkmcnt(10)
	v_mfma_f32_32x32x16_bf16 v[0:15], v[60:63], v[92:95], v[0:15]
	v_max3_f32 v49, v49, v70, v71
	v_max3_f32 v48, v48, v69, v100
	v_max3_f32 v49, v49, v102, v103
	s_waitcnt lgkmcnt(8)
	v_mfma_f32_32x32x16_bf16 v[16:31], v[180:183], v[92:95], v[16:31]
	v_max3_f32 v48, v48, v101, v72
	v_max3_f32 v49, v49, v74, v75
	v_max3_f32 v48, v48, v73, v104
	s_waitcnt lgkmcnt(6)
	v_mfma_f32_32x32x16_bf16 v[0:15], v[176:179], v[80:83], v[0:15]
	v_max3_f32 v49, v49, v106, v107
	v_max3_f32 v48, v48, v105, v76
	v_max3_f32 v49, v49, v78, v79
	s_waitcnt lgkmcnt(4)
	v_mfma_f32_32x32x16_bf16 v[16:31], v[172:175], v[80:83], v[16:31]
	v_max3_f32 v48, v48, v77, v108
	v_max3_f32 v49, v49, v110, v111
	v_max3_f32 v48, v48, v109, v49
	s_waitcnt lgkmcnt(2)
	v_mfma_f32_32x32x16_bf16 v[0:15], v[168:171], v[84:87], v[0:15]
	v_mov_b32_e32 v49, v48
	s_nop 1
	v_permlane32_swap_b32_e32 v48, v49
	s_waitcnt lgkmcnt(0)
	v_mfma_f32_32x32x16_bf16 v[16:31], v[164:167], v[84:87], v[16:31]
	s_andn2_b64 vcc, exec, s[8:9]
	s_cbranch_vccnz .LBB0_791
	s_and_b32 s14, s14, 3
	s_mul_i32 s8, s14, 0x3400
	s_add_i32 s17, s8, 0
	v_add_u32_e32 v50, s17, v205
	s_waitcnt vmcnt(1)
	ds_write_b128 v50, v[140:143]
	s_and_saveexec_b64 s[8:9], s[42:43]
	v_add_u32_e32 v50, s17, v227
	ds_write_b128 v50, v[136:139]
	s_or_b64 exec, exec, s[8:9]
	s_mulk_i32 s14, 0x3000
	v_add_u32_e32 v50, s14, v225
	s_waitcnt vmcnt(0)
	ds_write_b128 v50, v[156:159] offset:53248
	s_andn2_b64 vcc, exec, s[18:19]
	s_cbranch_vccz .LBB0_792
